# attention step loop: static s_setprio 1 for the softmax-first role waves (4-7), reset at loop exit
# baseline (speedup 1.0000x reference)
; #define RING_ISSUE(SI) do { int kbi = kb0 + (SI) * 32; if (kbi > kb_last) kbi = kb_last; const int slot = (SI) % 3; \
;           const h16* srcp = wave < 4 ? kbase + (size_t)kbi * LDH + k_src_off : vT + (size_t)(kbi >> 5) * 2048 + v_src_off; \
;           __builtin_amdgcn_global_load_lds((const unsigned*)srcp, (LAS unsigned*)(ring + slot * 8192 + stage_dst), 16, 0, 0); } while (0)
; DI void attn_phase(const Params& p, const int layer, const int wid_s) {
;     ...
; #pragma unroll 1
;         for (int si = 0; si < nsteps; ++si) {
;           asm volatile("s_waitcnt vmcnt(1) lgkmcnt(0)" ::: "memory");
;           __builtin_amdgcn_s_barrier();
;           asm volatile("" ::: "memory");
;           RING_ISSUE(si + 2);
;           const int kb = kb0 + si * 32;
;           if (kb > kmax_w || kb < lo_w) continue;
;           if (br == 1 && kb + 31 + 128 <= t0 && __ballot((selmask >> (kb >> 6)) & 1u) == 0ull) continue;
.LBB0_349:
	s_and_b64 vcc, exec, s[30:31]
	s_cbranch_vccz .Lat_ytop
	s_setprio 1
	s_branch .Lat_xtop

; template <bool SEL, bool GEN>
; DI void attn_step(const KF& kv, const int kb, const int t, const int lane, const bool selbit,
;                   const LAS float* tabh, const half8 (&q)[2][2], f32x4 (&O)[2][4], const float (&nR)[2], float (&l)[2]) {
;     ...
;     for (int j = 0; j < 4; ++j) { p0[j] = __builtin_amdgcn_exp2f(s[hp][0][j]); p1[j] = __builtin_amdgcn_exp2f(s[hp][1][j]); }
;     l[hp] += ((p0[0] + p0[1]) + (p0[2] + p0[3])) + ((p1[0] + p1[1]) + (p1[2] + p1[3]));
;     pf[hp] = pack8(p0, p1);
.Lat_done:
	s_setprio 0
	s_nop 7
	s_nop 7
	v_add_f32_e32 v214, v214, v215
	v_add_f32_e32 v216, v216, v217
	v_add_f32_e32 v218, v218, v219
	v_add_f32_e32 v220, v220, v221
	v_add_f32_e32 v2, v214, v216
	v_add_f32_e32 v3, v218, v220
	v_mov_b32_e32 v64, v60
	v_mov_b32_e32 v65, v61
	v_mov_b32_e32 v66, v62
	v_mov_b32_e32 v67, v63
	s_branch .LBB0_368
